# hyena unit loop: dwconv weights by scalar loads, no wait for previous unit's scattered stores at unit start/latch, queue atomic wait deferred to its use
# speedup vs baseline: 1.0080x; 1.0080x over previous
.LBB0_604:
	s_add_u32 s22, s90, 0x14918000
	s_addc_u32 s23, s91, 0
	s_add_u32 s24, s90, 0x21918000
	s_addc_u32 s25, s91, 0
	s_add_u32 s26, s90, 0x10518000
	s_addc_u32 s27, s91, 0
	s_mov_b32 s11, 0
	v_mov_b32_e32 v14, 0
	s_movk_i32 s28, 0x440
	s_movk_i32 s29, 0x5ff
	s_movk_i32 s30, 0x200
	s_mov_b32 s31, 0x78787879
	s_movk_i32 s34, 0x88
	s_movk_i32 s35, 0x43e
	s_movk_i32 s36, 0x910
	s_movk_i32 s37, 0xff78
	s_movk_i32 s38, 0x43f
	s_movk_i32 s39, 0x23f
	v_mov_b32_e32 v85, 0x3000
	v_mov_b32_e32 v86, 0x6000
	s_movk_i32 s40, 0x488
	v_mov_b32_e32 v87, 0x4000
	v_mov_b32_e32 v88, 0x7000
	v_mov_b32_e32 v89, 0x5000
	v_mov_b32_e32 v90, 0x8000
	s_movk_i32 s41, 0x1110
	s_movk_i32 s42, 0x220
	s_mov_b64 s[12:13], 0x1000
	s_mov_b64 s[14:15], 0x1800
	s_movk_i32 s43, 0x4880
	s_add_i32 s44, 0, 0x20008
	s_movk_i32 s45, 0x7ff
	s_movk_i32 s46, 0x100
	s_movk_i32 s47, 0x1100
	s_movk_i32 s48, 0x10fe
	s_movk_i32 s49, 0x310
	s_movk_i32 s50, 0x10ff
	s_movk_i32 s51, 0xeff
	s_movk_i32 s52, 0x188
	s_movk_i32 s53, 0x80
	s_movk_i32 s54, 0x510
	s_movk_i32 s55, 0xa20
	s_add_i32 s56, 0, 0xa1e0
	s_movk_i32 s57, 0x6200
	v_mov_b32_e32 v91, 0x2440
	v_mov_b32_e32 v92, 0x800
	v_mov_b32_e32 v93, 0x3100
	v_mov_b32_e32 v94, 0x280
	s_waitcnt vmcnt(0)
	s_branch .LBB0_607
.LBB0_605:
	s_waitcnt vmcnt(8)
	v_mov_b64_e32 v[26:27], v[4:5]
	v_mov_b64_e32 v[30:31], v[8:9]
	v_mov_b64_e32 v[34:35], v[12:13]
	v_mov_b64_e32 v[38:39], v[20:21]
	v_mov_b64_e32 v[24:25], v[2:3]
	v_mov_b64_e32 v[28:29], v[6:7]
	v_mov_b64_e32 v[32:33], v[10:11]
	v_mov_b32_e32 v97, v1
	v_mov_b32_e32 v105, v81
	v_mov_b32_e32 v107, v83
	v_mov_b32_e32 v96, v80
	v_mov_b32_e32 v104, v82
	v_mov_b32_e32 v106, v84
	v_mov_b64_e32 v[36:37], v[18:19]
.LBB0_606:
	s_waitcnt vmcnt(8)
	v_mov_b64_e32 v[2:3], v[24:25]
	v_mov_b64_e32 v[6:7], v[28:29]
	v_mov_b64_e32 v[10:11], v[32:33]
	v_mov_b64_e32 v[18:19], v[36:37]
	s_cmpk_lt_u32 s17, 0x800
	v_mov_b64_e32 v[4:5], v[26:27]
	v_mov_b64_e32 v[8:9], v[30:31]
	v_mov_b64_e32 v[12:13], v[34:35]
	v_mov_b32_e32 v1, v97
	v_mov_b32_e32 v81, v105
	v_mov_b32_e32 v83, v107
	v_mov_b32_e32 v80, v96
	v_mov_b32_e32 v82, v104
	v_mov_b32_e32 v84, v106
	v_mov_b64_e32 v[20:21], v[38:39]
	s_cbranch_scc0 .LBB0_730
.LBB0_607:
	s_lshr_b32 s0, s17, 10
	s_xor_b32 s0, s0, 1
	s_and_b32 s0, s0, 1
	s_and_b32 s16, s17, 0x3ff
	s_cmp_eq_u32 s0, 0
	s_mov_b64 s[0:1], -1
	s_cbranch_scc1 .LBB0_668
	v_mov_b32_e32 v22, v154
	v_mov_b32_e32 v95, 0
	v_cmp_eq_u32_e32 vcc, 0, v22
	s_and_saveexec_b64 s[0:1], vcc
	s_cbranch_execz .LBB0_612
	s_mov_b64 s[4:5], exec
	v_mbcnt_lo_u32_b32 v15, s4, 0
	v_mbcnt_hi_u32_b32 v15, s5, v15
	v_cmp_eq_u32_e32 vcc, 0, v15
	s_and_saveexec_b64 s[2:3], vcc
	s_cbranch_execz .LBB0_611
	s_bcnt1_i32_b64 s4, s[4:5]
	v_mov_b32_e32 v16, s4
	v_readlane_b32 s4, v232, 2
	v_readlane_b32 s5, v232, 3
	s_nop 4
	global_atomic_add v95, v14, v16, s[4:5] sc0
.LBB0_611:
	s_or_b64 exec, exec, s[2:3]
.LBB0_612:
	s_or_b64 exec, exec, s[0:1]
	v_cmp_gt_i32_e32 vcc, s28, v22
	s_and_saveexec_b64 s[0:1], vcc
	s_cbranch_execz .LBB0_624
	s_cmp_eq_u32 s98, 1
	s_cbranch_scc1 .LBB0_624
	v_max_i32_e32 v15, 0x240, v22
	v_sub_u32_e32 v15, v15, v22
	v_add_u32_e32 v15, 0x1ff, v15
	v_cmp_lt_u32_e32 vcc, s29, v15
	s_mov_b64 s[4:5], -1
	v_mov_b32_e32 v16, v22
	s_and_saveexec_b64 s[2:3], vcc
	s_cbranch_execz .LBB0_621
	v_lshrrev_b32_e32 v15, 9, v15
	v_add_u32_e32 v25, 0x600, v22
	v_add_u32_e32 v24, 0x400, v22
	v_add_u32_e32 v23, 0x200, v22
	v_add_u32_e32 v16, -3, v15
	v_mov_b64_e32 v[28:29], v[24:25]
	v_cmp_lt_u32_e32 vcc, 3, v16
	v_mov_b64_e32 v[26:27], v[22:23]
	s_and_saveexec_b64 s[18:19], vcc
	s_cbranch_execz .LBB0_618
	v_lshrrev_b32_e32 v17, 2, v16
	v_add_u32_e32 v17, 1, v17
	v_mov_b64_e32 v[28:29], v[24:25]
	v_and_b32_e32 v17, 0x7ffffffe, v17
	s_mov_b64 s[20:21], 0
	v_mov_b64_e32 v[26:27], v[22:23]

.LBB0_624:
	s_or_b64 exec, exec, s[0:1]
	s_load_dwordx4 s[4:7], s[92:93], 0x70
	s_mov_b32 s17, s11
	s_lshl_b64 s[2:3], s[16:17], 2
	v_bfe_i32 v23, v22, 28, 1
	v_lshlrev_b32_e32 v15, 3, v22
	s_waitcnt lgkmcnt(0)
	s_add_u32 s0, s4, s2
	s_addc_u32 s1, s5, s3
	s_load_dword s60, s[0:1], 0x0
	s_load_dword s61, s[0:1], 0x6000
	s_load_dword s62, s[0:1], 0x3000
	s_add_u32 s2, s6, s2
	s_addc_u32 s3, s7, s3
	s_load_dword s63, s[2:3], 0x0
	s_or_b32 s10, s16, 0x400
	s_load_dword s64, s[0:1], 0x4000
	s_load_dword s65, s[0:1], 0x7000
	s_lshl_b64 s[2:3], s[10:11], 2
	s_add_u32 s8, s4, s2
	s_addc_u32 s9, s5, s3
	s_load_dword s66, s[8:9], 0x0
	s_add_u32 s2, s6, s2
	s_addc_u32 s3, s7, s3
	s_load_dword s67, s[2:3], 0x0
	s_or_b32 s10, s16, 0x800
	s_load_dword s68, s[0:1], 0x5000
	s_load_dword s69, s[0:1], 0x8000
	s_lshl_b64 s[0:1], s[10:11], 2
	s_add_u32 s2, s4, s0
	s_addc_u32 s3, s5, s1
	s_add_u32 s0, s6, s0
	s_addc_u32 s1, s7, s1
	s_load_dword s70, s[2:3], 0x0
	s_load_dword s71, s[0:1], 0x0
	v_ashrrev_i32_e32 v16, 31, v22
	v_lshrrev_b32_e32 v23, 22, v23
	v_lshrrev_b32_e32 v26, 25, v16
	v_add_u32_e32 v23, v15, v23
	v_add_u32_e32 v26, v22, v26
	v_and_b32_e32 v23, 0xfffffc00, v23
	s_waitcnt lgkmcnt(0)
	v_mov_b32_e32 v25, s60
	v_mov_b32_e32 v24, s61
	v_mov_b32_e32 v27, s62
	v_mov_b32_e32 v17, s63
	v_mov_b32_e32 v37, s64
	v_mov_b32_e32 v38, s65
	v_mov_b32_e32 v39, s66
	v_mov_b32_e32 v58, s67
	v_mov_b32_e32 v47, s68
	v_mov_b32_e32 v48, s69
	v_mov_b32_e32 v49, s70
	v_mov_b32_e32 v60, s71
	v_and_b32_e32 v30, 0xffff0000, v2
	v_ashrrev_i32_e32 v59, 7, v26
	v_sub_u32_e32 v36, v15, v23
	v_lshlrev_b32_e32 v29, 16, v1
	v_lshlrev_b32_e32 v32, 16, v3
	v_and_b32_e32 v35, 0xffff0000, v5
	v_and_b32_e32 v34, 0xffff0000, v4
	v_lshlrev_b32_e32 v41, 16, v5
	v_lshlrev_b32_e32 v40, 16, v80
	v_mov_b32_e32 v28, v30
	v_lshlrev_b32_e32 v23, 11, v59
	v_lshlrev_b32_e32 v26, 1, v36
	v_lshlrev_b32_e32 v46, 16, v2
	v_and_b32_e32 v31, 0xffff0000, v3
	v_mov_b32_e32 v42, v32
	v_mov_b32_e32 v43, v30
	v_pk_mov_b32 v[44:45], v[40:41], v[34:35] op_sel:[1,0]
	v_add3_u32 v23, 0, v23, v26
	v_lshlrev_b32_e32 v33, 16, v4
	v_cmp_gt_i32_e32 vcc, s30, v22
	v_mov_b32_e32 v50, v25
	v_pk_mul_f32 v[28:29], v[24:25], v[28:29]
	v_mov_b32_e32 v51, v24
	v_mov_b32_e32 v26, v24
	v_pk_mul_f32 v[52:53], v[24:25], v[40:41]
	v_fma_f32 v29, v27, v46, v29
	v_pk_mul_f32 v[54:55], v[50:51], v[30:31]
	v_pk_mul_f32 v[42:43], v[26:27], v[42:43]
	v_mov_b32_e32 v30, v34
	v_pk_mul_f32 v[44:45], v[26:27], v[44:45]
	v_pk_mul_f32 v[56:57], v[50:51], v[32:33]
	v_pk_mul_f32 v[50:51], v[50:51], v[34:35]
	v_fma_f32 v26, v27, v35, v53
	v_add_f32_e32 v34, v28, v29
	v_fma_f32 v35, v25, v46, v43
	v_pk_mul_f32 v[28:29], v[24:25], v[30:31]
	v_fma_f32 v24, v25, v33, v45
	v_fma_f32 v32, v27, v32, v54
	v_fma_f32 v40, v27, v31, v56
	v_fma_f32 v25, v27, v41, v50
	v_add_f32_e32 v31, v42, v35
	v_fma_f32 v27, v27, v33, v29
	v_add_f32_e32 v24, v44, v24
	v_add_f32_e32 v26, v52, v26
	v_add_f32_e32 v30, v17, v34
	v_add_f32_e32 v32, v55, v32
	v_add_f32_e32 v34, v57, v40
	v_add_f32_e32 v25, v51, v25
	v_add_f32_e32 v29, v17, v31
	v_add_f32_e32 v27, v28, v27
	v_add_f32_e32 v28, v17, v24
	v_add_f32_e32 v31, v17, v32
	v_add_f32_e32 v32, v17, v34
	v_add_f32_e32 v33, v17, v25
	v_add_f32_e32 v27, v17, v27
	v_add_f32_e32 v17, v17, v26
	v_cvt_pk_bf16_f32 v24, v30, v29
	v_cvt_pk_bf16_f32 v26, v27, v28
	v_mad_u64_u32 v[28:29], s[0:1], v59, s40, v[36:37]
	v_cvt_pk_bf16_f32 v27, v33, v17
	v_lshl_add_u32 v17, v28, 1, 0
	v_cvt_pk_bf16_f32 v25, v31, v32
	ds_write_b128 v17, v[24:27] offset:128
	v_and_b32_e32 v26, 0xffff0000, v6
	v_lshlrev_b32_e32 v25, 16, v81
	v_mov_b32_e32 v24, v26
	v_lshlrev_b32_e32 v17, 16, v6
	v_pk_mul_f32 v[24:25], v[38:39], v[24:25]
	v_and_b32_e32 v27, 0xffff0000, v7
	v_fma_f32 v25, v37, v17, v25
	v_add_f32_e32 v24, v24, v25
	v_add_f32_e32 v34, v58, v24
	v_mov_b32_e32 v24, v39
	v_mov_b32_e32 v25, v38
	v_pk_mul_f32 v[28:29], v[24:25], v[26:27]
	v_lshlrev_b32_e32 v30, 16, v7
	v_lshlrev_b32_e32 v31, 16, v8
	v_mov_b32_e32 v33, v26
	v_fma_f32 v26, v37, v30, v28
	v_add_f32_e32 v26, v29, v26
	v_pk_mul_f32 v[28:29], v[24:25], v[30:31]
	v_add_f32_e32 v35, v58, v26
	v_fma_f32 v26, v37, v27, v28
	v_add_f32_e32 v26, v29, v26
	v_and_b32_e32 v28, 0xffff0000, v8
	v_mov_b32_e32 v32, v30
	v_add_f32_e32 v30, v58, v26
	v_mov_b32_e32 v26, v28
	v_pk_mul_f32 v[26:27], v[38:39], v[26:27]
	v_mov_b32_e32 v36, v38
	v_fma_f32 v27, v37, v31, v27
	v_pk_mul_f32 v[32:33], v[36:37], v[32:33]
	v_and_b32_e32 v29, 0xffff0000, v9
	v_add_f32_e32 v26, v26, v27
	v_fma_f32 v17, v39, v17, v33
	v_add_f32_e32 v40, v58, v26
	v_pk_mul_f32 v[24:25], v[24:25], v[28:29]
	v_lshlrev_b32_e32 v27, 16, v9
	v_lshlrev_b32_e32 v26, 16, v82
	v_add_f32_e32 v17, v32, v17
	v_pk_mov_b32 v[32:33], v[26:27], v[28:29] op_sel:[1,0]
	v_fma_f32 v24, v37, v27, v24
	v_pk_mul_f32 v[32:33], v[36:37], v[32:33]
	v_add_f32_e32 v24, v25, v24
	v_fma_f32 v28, v39, v31, v33
	v_add_f32_e32 v31, v58, v24
	v_pk_mul_f32 v[24:25], v[38:39], v[26:27]
	v_add_f32_e32 v28, v32, v28
	v_fma_f32 v25, v37, v29, v25
	v_add_f32_e32 v24, v24, v25
	v_add_f32_e32 v28, v58, v28
	v_add_f32_e32 v27, v58, v24
	v_cvt_pk_bf16_f32 v26, v40, v28
	v_add_f32_e32 v17, v58, v17
	v_cvt_pk_bf16_f32 v24, v34, v17
	v_cvt_pk_bf16_f32 v25, v35, v30
	v_cvt_pk_bf16_f32 v27, v31, v27
	ds_write_b128 v23, v[24:27] offset:18560
	v_and_b32_e32 v26, 0xffff0000, v10
	v_lshlrev_b32_e32 v25, 16, v83
	v_mov_b32_e32 v24, v26
	v_lshlrev_b32_e32 v17, 16, v10
	v_pk_mul_f32 v[24:25], v[48:49], v[24:25]
	v_and_b32_e32 v27, 0xffff0000, v11
	v_fma_f32 v25, v47, v17, v25
	v_add_f32_e32 v24, v24, v25
	v_add_f32_e32 v34, v60, v24
	v_mov_b32_e32 v24, v49
	v_mov_b32_e32 v25, v48
	v_pk_mul_f32 v[28:29], v[24:25], v[26:27]
	v_lshlrev_b32_e32 v30, 16, v11
	v_lshlrev_b32_e32 v31, 16, v12
	v_mov_b32_e32 v33, v26
	v_fma_f32 v26, v47, v30, v28
	v_add_f32_e32 v26, v29, v26
	v_pk_mul_f32 v[28:29], v[24:25], v[30:31]
	v_add_f32_e32 v35, v60, v26
	v_fma_f32 v26, v47, v27, v28
	v_add_f32_e32 v26, v29, v26
	v_and_b32_e32 v28, 0xffff0000, v12
	v_mov_b32_e32 v32, v30
	v_add_f32_e32 v30, v60, v26
	v_mov_b32_e32 v26, v28
	v_pk_mul_f32 v[26:27], v[48:49], v[26:27]
	v_mov_b32_e32 v46, v48
	v_fma_f32 v27, v47, v31, v27
	v_pk_mul_f32 v[32:33], v[46:47], v[32:33]
	v_and_b32_e32 v29, 0xffff0000, v13
	v_add_f32_e32 v26, v26, v27
	v_fma_f32 v17, v49, v17, v33
	v_add_f32_e32 v36, v60, v26
	v_pk_mul_f32 v[24:25], v[24:25], v[28:29]
	v_lshlrev_b32_e32 v27, 16, v13
	v_lshlrev_b32_e32 v26, 16, v84
	v_add_f32_e32 v17, v32, v17
	v_pk_mov_b32 v[32:33], v[26:27], v[28:29] op_sel:[1,0]
	v_fma_f32 v24, v47, v27, v24
	v_pk_mul_f32 v[32:33], v[46:47], v[32:33]
	v_add_f32_e32 v24, v25, v24
	v_fma_f32 v28, v49, v31, v33
	v_add_f32_e32 v31, v60, v24
	v_pk_mul_f32 v[24:25], v[48:49], v[26:27]
	v_add_f32_e32 v28, v32, v28
	v_fma_f32 v25, v47, v29, v25
	v_add_f32_e32 v24, v24, v25
	v_add_f32_e32 v27, v60, v24
	v_add_f32_e32 v17, v60, v17
	v_add_f32_e32 v28, v60, v28
	v_cvt_pk_bf16_f32 v24, v34, v17
	v_cvt_pk_bf16_f32 v25, v35, v30
	v_cvt_pk_bf16_f32 v26, v36, v28
	v_cvt_pk_bf16_f32 v27, v31, v27
	ds_write_b128 v23, v[24:27] offset:26752
	s_and_saveexec_b64 s[0:1], vcc
	s_cbranch_execz .LBB0_626
	v_add_u32_sdwa v16, v22, v16 dst_sel:DWORD dst_unused:UNUSED_PAD src0_sel:DWORD src1_sel:BYTE_3
	v_ashrrev_i32_e32 v16, 8, v16
	v_lshlrev_b32_e32 v17, 11, v16
	v_sub_u32_e32 v15, v15, v17
	v_mad_i32_i24 v17, v16, s41, v15
	v_mul_i32_i24_e32 v16, 0x2220, v16
	v_lshlrev_b32_e32 v15, 1, v15
	v_lshl_add_u32 v17, v17, 1, 0
	v_add3_u32 v15, 0, v16, v15
	ds_write_b128 v17, v[18:21] offset:35072
	ds_write_b128 v15, v[18:21] offset:39438

.LBB0_648:
	v_mov_b32_e32 v15, s44
	s_cbranch_execz .Lhyf_nowait_607_0
	s_waitcnt vmcnt(0)
.Lhyf_nowait_607_0:
	ds_write_b32 v15, v95

.LBB0_668:
	s_and_b64 vcc, exec, s[0:1]
	s_cbranch_vccz .LBB0_606
	v_mov_b32_e32 v22, v154
	v_mov_b32_e32 v44, 0
	v_cmp_eq_u32_e32 vcc, 0, v22
	s_and_saveexec_b64 s[0:1], vcc
	s_cbranch_execz .LBB0_673
	s_mov_b64 s[4:5], exec
	v_mbcnt_lo_u32_b32 v15, s4, 0
	v_mbcnt_hi_u32_b32 v15, s5, v15
	v_cmp_eq_u32_e32 vcc, 0, v15
	s_and_saveexec_b64 s[2:3], vcc
	s_cbranch_execz .LBB0_672
	s_bcnt1_i32_b64 s4, s[4:5]
	v_mov_b32_e32 v16, s4
	v_readlane_b32 s4, v232, 2
	v_readlane_b32 s5, v232, 3
	s_nop 4
	global_atomic_add v44, v14, v16, s[4:5] sc0
.LBB0_672:
	s_or_b64 exec, exec, s[2:3]
.LBB0_673:
	s_or_b64 exec, exec, s[0:1]
	v_cmp_gt_i32_e32 vcc, s47, v22
	s_and_saveexec_b64 s[0:1], vcc
	s_cbranch_execz .LBB0_685
	s_cmp_eq_u32 s98, 2
	s_cbranch_scc1 .LBB0_685
	v_max_i32_e32 v15, 0xf00, v22
	v_sub_u32_e32 v15, v15, v22
	v_add_u32_e32 v15, 0x1ff, v15
	v_cmp_lt_u32_e32 vcc, s29, v15
	s_mov_b64 s[4:5], -1
	v_mov_b32_e32 v16, v22
	s_and_saveexec_b64 s[2:3], vcc
	s_cbranch_execz .LBB0_682
	v_lshrrev_b32_e32 v15, 9, v15
	s_waitcnt vmcnt(2)
	v_add_u32_e32 v25, 0x600, v22
	v_add_u32_e32 v24, 0x400, v22
	v_add_u32_e32 v23, 0x200, v22
	v_add_u32_e32 v16, -3, v15
	s_waitcnt vmcnt(1)
	v_mov_b64_e32 v[28:29], v[24:25]
	v_cmp_lt_u32_e32 vcc, 3, v16
	v_mov_b64_e32 v[26:27], v[22:23]
	s_and_saveexec_b64 s[18:19], vcc
	s_cbranch_execz .LBB0_679
	v_lshrrev_b32_e32 v17, 2, v16
	v_add_u32_e32 v17, 1, v17
	v_mov_b64_e32 v[28:29], v[24:25]
	v_and_b32_e32 v17, 0x7ffffffe, v17
	s_mov_b64 s[20:21], 0
	v_mov_b64_e32 v[26:27], v[22:23]

.LBB0_685:
	s_or_b64 exec, exec, s[0:1]
	s_load_dwordx4 s[4:7], s[92:93], 0x70
	s_mov_b32 s17, s11
	s_lshl_b64 s[2:3], s[16:17], 2
	v_lshlrev_b32_e32 v15, 3, v22
	v_ashrrev_i32_e32 v16, 31, v22
	s_waitcnt lgkmcnt(0)
	s_add_u32 s0, s4, s2
	s_addc_u32 s1, s5, s3
	s_load_dword s60, s[0:1], 0x0
	s_load_dword s61, s[0:1], 0x6000
	s_load_dword s62, s[0:1], 0x3000
	s_add_u32 s2, s6, s2
	s_addc_u32 s3, s7, s3
	s_load_dword s63, s[2:3], 0x0
	s_or_b32 s10, s16, 0x400
	s_load_dword s64, s[0:1], 0x4000
	s_load_dword s65, s[0:1], 0x7000
	s_lshl_b64 s[2:3], s[10:11], 2
	s_add_u32 s8, s4, s2
	s_addc_u32 s9, s5, s3
	s_load_dword s66, s[8:9], 0x0
	s_add_u32 s2, s6, s2
	s_addc_u32 s3, s7, s3
	s_load_dword s67, s[2:3], 0x0
	s_or_b32 s10, s16, 0x800
	s_load_dword s68, s[0:1], 0x5000
	s_load_dword s69, s[0:1], 0x8000
	s_lshl_b64 s[0:1], s[10:11], 2
	s_add_u32 s2, s4, s0
	s_addc_u32 s3, s5, s1
	s_add_u32 s0, s6, s0
	s_addc_u32 s1, s7, s1
	s_load_dword s70, s[2:3], 0x0
	s_load_dword s71, s[0:1], 0x0
	v_bfe_i32 v23, v22, 28, 1
	s_waitcnt lgkmcnt(0)
	v_mov_b32_e32 v25, s60
	v_mov_b32_e32 v24, s61
	v_mov_b32_e32 v27, s62
	v_mov_b32_e32 v17, s63
	v_mov_b32_e32 v35, s64
	v_mov_b32_e32 v36, s65
	v_mov_b32_e32 v37, s66
	v_mov_b32_e32 v48, s67
	v_mov_b32_e32 v49, s68
	v_mov_b32_e32 v50, s69
	v_mov_b32_e32 v51, s70
	v_mov_b32_e32 v61, s71
	v_lshrrev_b32_e32 v26, 27, v16
	v_add_u32_sdwa v23, v15, v23 dst_sel:DWORD dst_unused:UNUSED_PAD src0_sel:DWORD src1_sel:BYTE_3
	v_add_u32_e32 v26, v22, v26
	v_and_b32_e32 v23, 0xffffff00, v23
	v_and_b32_e32 v30, 0xffff0000, v2
	v_ashrrev_i32_e32 v60, 5, v26
	v_sub_u32_e32 v34, v15, v23
	v_lshlrev_b32_e32 v29, 16, v1
	v_lshlrev_b32_e32 v32, 16, v3
	v_and_b32_e32 v39, 0xffff0000, v5
	v_and_b32_e32 v38, 0xffff0000, v4
	v_lshlrev_b32_e32 v41, 16, v5
	v_lshlrev_b32_e32 v40, 16, v80
	v_mov_b32_e32 v28, v30
	v_lshlrev_b32_e32 v23, 9, v60
	v_lshlrev_b32_e32 v26, 1, v34
	v_lshlrev_b32_e32 v45, 16, v2
	v_and_b32_e32 v31, 0xffff0000, v3
	v_mov_b32_e32 v42, v32
	v_mov_b32_e32 v43, v30
	v_pk_mov_b32 v[46:47], v[40:41], v[38:39] op_sel:[1,0]
	v_add3_u32 v23, 0, v23, v26
	v_lshlrev_b32_e32 v33, 16, v4
	v_cmp_gt_i32_e32 vcc, s53, v22
	v_mov_b32_e32 v52, v25
	v_pk_mul_f32 v[28:29], v[24:25], v[28:29]
	v_mov_b32_e32 v53, v24
	v_mov_b32_e32 v26, v24
	v_pk_mul_f32 v[54:55], v[24:25], v[40:41]
	v_fma_f32 v29, v27, v45, v29
	v_pk_mul_f32 v[56:57], v[52:53], v[30:31]
	v_pk_mul_f32 v[42:43], v[26:27], v[42:43]
	v_mov_b32_e32 v30, v38
	v_pk_mul_f32 v[46:47], v[26:27], v[46:47]
	v_pk_mul_f32 v[58:59], v[52:53], v[32:33]
	v_pk_mul_f32 v[52:53], v[52:53], v[38:39]
	v_fma_f32 v26, v27, v39, v55
	v_add_f32_e32 v38, v28, v29
	v_fma_f32 v39, v25, v45, v43
	v_pk_mul_f32 v[28:29], v[24:25], v[30:31]
	v_fma_f32 v24, v25, v33, v47
	v_fma_f32 v32, v27, v32, v56
	v_fma_f32 v40, v27, v31, v58
	v_fma_f32 v25, v27, v41, v52
	v_add_f32_e32 v26, v54, v26
	v_add_f32_e32 v31, v42, v39
	v_fma_f32 v27, v27, v33, v29
	v_add_f32_e32 v24, v46, v24
	v_add_f32_e32 v30, v17, v38
	v_add_f32_e32 v32, v57, v32
	v_add_f32_e32 v38, v59, v40
	v_add_f32_e32 v25, v53, v25
	v_add_f32_e32 v29, v17, v26
	v_add_f32_e32 v26, v17, v31
	v_add_f32_e32 v27, v28, v27
	v_add_f32_e32 v28, v17, v24
	v_add_f32_e32 v31, v17, v32
	v_add_f32_e32 v32, v17, v38
	v_add_f32_e32 v33, v17, v25
	v_add_f32_e32 v17, v17, v27
	v_cvt_pk_bf16_f32 v24, v30, v26
	v_cvt_pk_bf16_f32 v26, v17, v28
	v_cvt_pk_bf16_f32 v27, v33, v29
	v_mad_u64_u32 v[28:29], s[0:1], v60, s52, v[34:35]
	v_lshl_add_u32 v17, v28, 1, 0
	v_cvt_pk_bf16_f32 v25, v31, v32
	ds_write_b128 v17, v[24:27] offset:128
	v_and_b32_e32 v26, 0xffff0000, v6
	v_lshlrev_b32_e32 v25, 16, v81
	v_mov_b32_e32 v24, v26
	v_lshlrev_b32_e32 v17, 16, v6
	v_pk_mul_f32 v[24:25], v[36:37], v[24:25]
	v_and_b32_e32 v27, 0xffff0000, v7
	v_fma_f32 v25, v35, v17, v25
	v_add_f32_e32 v24, v24, v25
	v_add_f32_e32 v38, v48, v24
	v_mov_b32_e32 v24, v37
	v_mov_b32_e32 v25, v36
	v_pk_mul_f32 v[28:29], v[24:25], v[26:27]
	v_lshlrev_b32_e32 v30, 16, v7
	v_lshlrev_b32_e32 v31, 16, v8
	v_mov_b32_e32 v33, v26
	v_fma_f32 v26, v35, v30, v28
	v_add_f32_e32 v26, v29, v26
	v_pk_mul_f32 v[28:29], v[24:25], v[30:31]
	v_add_f32_e32 v39, v48, v26
	v_fma_f32 v26, v35, v27, v28
	v_add_f32_e32 v26, v29, v26
	v_and_b32_e32 v28, 0xffff0000, v8
	v_mov_b32_e32 v32, v30
	v_add_f32_e32 v30, v48, v26
	v_mov_b32_e32 v26, v28
	v_pk_mul_f32 v[26:27], v[36:37], v[26:27]
	v_mov_b32_e32 v34, v36
	v_fma_f32 v27, v35, v31, v27
	v_pk_mul_f32 v[32:33], v[34:35], v[32:33]
	v_and_b32_e32 v29, 0xffff0000, v9
	v_add_f32_e32 v26, v26, v27
	v_fma_f32 v17, v37, v17, v33
	v_add_f32_e32 v40, v48, v26
	v_pk_mul_f32 v[24:25], v[24:25], v[28:29]
	v_lshlrev_b32_e32 v27, 16, v9
	v_lshlrev_b32_e32 v26, 16, v82
	v_add_f32_e32 v17, v32, v17
	v_pk_mov_b32 v[32:33], v[26:27], v[28:29] op_sel:[1,0]
	v_fma_f32 v24, v35, v27, v24
	v_pk_mul_f32 v[32:33], v[34:35], v[32:33]
	v_add_f32_e32 v24, v25, v24
	v_fma_f32 v28, v37, v31, v33
	v_add_f32_e32 v31, v48, v24
	v_pk_mul_f32 v[24:25], v[36:37], v[26:27]
	v_add_f32_e32 v28, v32, v28
	v_fma_f32 v25, v35, v29, v25
	v_add_f32_e32 v24, v24, v25
	v_add_f32_e32 v28, v48, v28
	v_add_f32_e32 v27, v48, v24
	v_cvt_pk_bf16_f32 v26, v40, v28
	v_add_f32_e32 v17, v48, v17
	v_cvt_pk_bf16_f32 v24, v38, v17
	v_cvt_pk_bf16_f32 v25, v39, v30
	v_cvt_pk_bf16_f32 v27, v31, v27
	ds_write_b128 v23, v[24:27] offset:25088
	v_and_b32_e32 v26, 0xffff0000, v10
	v_lshlrev_b32_e32 v25, 16, v83
	v_mov_b32_e32 v24, v26
	v_lshlrev_b32_e32 v17, 16, v10
	v_pk_mul_f32 v[24:25], v[50:51], v[24:25]
	v_and_b32_e32 v27, 0xffff0000, v11
	v_fma_f32 v25, v49, v17, v25
	v_add_f32_e32 v24, v24, v25
	v_add_f32_e32 v34, v61, v24
	v_mov_b32_e32 v24, v51
	v_mov_b32_e32 v25, v50
	v_pk_mul_f32 v[28:29], v[24:25], v[26:27]
	v_lshlrev_b32_e32 v30, 16, v11
	v_lshlrev_b32_e32 v31, 16, v12
	v_mov_b32_e32 v33, v26
	v_fma_f32 v26, v49, v30, v28
	v_add_f32_e32 v26, v29, v26
	v_pk_mul_f32 v[28:29], v[24:25], v[30:31]
	v_add_f32_e32 v35, v61, v26
	v_fma_f32 v26, v49, v27, v28
	v_add_f32_e32 v26, v29, v26
	v_and_b32_e32 v28, 0xffff0000, v12
	v_mov_b32_e32 v32, v30
	v_add_f32_e32 v30, v61, v26
	v_mov_b32_e32 v26, v28
	v_pk_mul_f32 v[26:27], v[50:51], v[26:27]
	v_mov_b32_e32 v48, v50
	v_fma_f32 v27, v49, v31, v27
	v_pk_mul_f32 v[32:33], v[48:49], v[32:33]
	v_and_b32_e32 v29, 0xffff0000, v13
	v_add_f32_e32 v26, v26, v27
	v_fma_f32 v17, v51, v17, v33
	v_add_f32_e32 v36, v61, v26
	v_pk_mul_f32 v[24:25], v[24:25], v[28:29]
	v_lshlrev_b32_e32 v27, 16, v13
	v_lshlrev_b32_e32 v26, 16, v84
	v_add_f32_e32 v17, v32, v17
	v_pk_mov_b32 v[32:33], v[26:27], v[28:29] op_sel:[1,0]
	v_fma_f32 v24, v49, v27, v24
	v_pk_mul_f32 v[32:33], v[48:49], v[32:33]
	v_add_f32_e32 v24, v25, v24
	v_fma_f32 v28, v51, v31, v33
	v_add_f32_e32 v31, v61, v24
	v_pk_mul_f32 v[24:25], v[50:51], v[26:27]
	v_add_f32_e32 v28, v32, v28
	v_fma_f32 v25, v49, v29, v25
	v_add_f32_e32 v24, v24, v25
	v_add_f32_e32 v27, v61, v24
	v_add_f32_e32 v17, v61, v17
	v_add_f32_e32 v28, v61, v28
	v_cvt_pk_bf16_f32 v24, v34, v17
	v_cvt_pk_bf16_f32 v25, v35, v30
	v_cvt_pk_bf16_f32 v26, v36, v28
	v_cvt_pk_bf16_f32 v27, v31, v27
	ds_write_b128 v23, v[24:27] offset:33280
	s_and_saveexec_b64 s[0:1], vcc
	s_cbranch_execz .LBB0_687
	v_lshrrev_b32_e32 v16, 26, v16
	v_add_u32_e32 v16, v22, v16
	v_ashrrev_i32_e32 v17, 6, v16
	v_lshlrev_b32_e32 v16, 9, v17
	v_sub_u32_e32 v16, v15, v16
	v_mad_u64_u32 v[24:25], s[2:3], v17, s54, v[16:17]
	v_lshl_add_u32 v15, v24, 1, 0
	ds_write_b128 v15, v[18:21] offset:41600
	v_mul_lo_u32 v15, v17, s55
	v_lshlrev_b32_e32 v16, 1, v16
	v_add3_u32 v15, 0, v15, v16
	ds_write_b128 v15, v[18:21] offset:42894

.Lhyf_nowait_607_1:
	ds_write_b32 v15, v44

.LBB0_1845:
	s_add_u32 s24, s90, 0x14918000
	s_addc_u32 s25, s91, 0
	s_add_u32 s26, s90, 0x21918000
	s_addc_u32 s27, s91, 0
	s_add_u32 s28, s90, 0x10f18000
	s_addc_u32 s29, s91, 0
	s_mov_b32 s13, 0
	v_mov_b32_e32 v14, 0
	s_movk_i32 s30, 0x440
	s_movk_i32 s31, 0x5ff
	s_movk_i32 s34, 0x200
	s_mov_b32 s35, 0x78787879
	s_movk_i32 s36, 0x88
	s_movk_i32 s37, 0x43e
	s_movk_i32 s38, 0x910
	s_movk_i32 s39, 0xff78
	s_movk_i32 s40, 0x43f
	s_movk_i32 s41, 0x23f
	v_mov_b32_e32 v85, 0x9000
	v_mov_b32_e32 v86, 0xc000
	v_mov_b32_e32 v87, 0xf000
	v_mov_b32_e32 v88, 0x3000
	s_movk_i32 s42, 0x488
	v_mov_b32_e32 v89, 0xa000
	v_mov_b32_e32 v90, 0xd000
	v_mov_b32_e32 v91, 0x10000
	v_mov_b32_e32 v92, 0x4000
	v_mov_b32_e32 v93, 0xb000
	v_mov_b32_e32 v94, 0xe000
	v_mov_b32_e32 v95, 0x11000
	v_mov_b32_e32 v96, 0x5000
	s_movk_i32 s43, 0x1110
	s_movk_i32 s44, 0x220
	s_mov_b64 s[14:15], 0x1000
	s_mov_b64 s[16:17], 0x1800
	v_mov_b32_e32 v97, 0x2000
	s_movk_i32 s45, 0x4880
	s_add_i32 s46, 0, 0x20008
	s_movk_i32 s47, 0x7ff
	s_movk_i32 s48, 0x100
	s_movk_i32 s49, 0x1100
	s_movk_i32 s50, 0x10fe
	s_movk_i32 s51, 0x310
	s_movk_i32 s52, 0x10ff
	s_movk_i32 s53, 0xeff
	s_movk_i32 s54, 0x188
	s_movk_i32 s55, 0x80
	s_movk_i32 s56, 0x510
	s_movk_i32 s57, 0xa20
	s_add_i32 s58, 0, 0xa1e0
	s_movk_i32 s59, 0x6200
	v_mov_b32_e32 v98, 0x2440
	v_mov_b32_e32 v99, 0x800
	v_mov_b32_e32 v100, 0x3100
	v_mov_b32_e32 v101, 0x280
	s_waitcnt vmcnt(0)
	s_branch .LBB0_1848
.LBB0_1846:
	s_waitcnt vmcnt(8)
	v_mov_b64_e32 v[26:27], v[4:5]
	v_mov_b64_e32 v[30:31], v[8:9]
	v_mov_b64_e32 v[34:35], v[12:13]
	v_mov_b64_e32 v[38:39], v[20:21]
	v_mov_b64_e32 v[24:25], v[2:3]
	v_mov_b64_e32 v[28:29], v[6:7]
	v_mov_b64_e32 v[32:33], v[10:11]
	v_mov_b32_e32 v104, v1
	v_mov_b32_e32 v112, v81
	v_mov_b32_e32 v114, v83
	v_mov_b32_e32 v103, v80
	v_mov_b32_e32 v111, v82
	v_mov_b32_e32 v113, v84
	v_mov_b64_e32 v[36:37], v[18:19]
.LBB0_1847:
	s_waitcnt vmcnt(8)
	v_mov_b64_e32 v[2:3], v[24:25]
	v_mov_b64_e32 v[6:7], v[28:29]
	v_mov_b64_e32 v[10:11], v[32:33]
	v_mov_b64_e32 v[18:19], v[36:37]
	s_cmpk_lt_u32 s19, 0x800
	v_mov_b64_e32 v[4:5], v[26:27]
	v_mov_b64_e32 v[8:9], v[30:31]
	v_mov_b64_e32 v[12:13], v[34:35]
	v_mov_b32_e32 v1, v104
	v_mov_b32_e32 v81, v112
	v_mov_b32_e32 v83, v114
	v_mov_b32_e32 v80, v103
	v_mov_b32_e32 v82, v111
	v_mov_b32_e32 v84, v113
	v_mov_b64_e32 v[20:21], v[38:39]
	s_cbranch_scc0 .LBB0_1971
.LBB0_1848:
	s_lshr_b32 s0, s19, 10
	s_xor_b32 s0, s0, 1
	s_and_b32 s0, s0, 1
	s_and_b32 s18, s19, 0x3ff
	s_cmp_eq_u32 s0, 0
	s_mov_b64 s[0:1], -1
	s_cbranch_scc1 .LBB0_1909
	v_mov_b32_e32 v22, v154
	v_mov_b32_e32 v102, 0
	v_cmp_eq_u32_e32 vcc, 0, v22
	s_and_saveexec_b64 s[0:1], vcc
	s_cbranch_execz .LBB0_1853
	s_mov_b64 s[4:5], exec
	v_mbcnt_lo_u32_b32 v15, s4, 0
	v_mbcnt_hi_u32_b32 v15, s5, v15
	v_cmp_eq_u32_e32 vcc, 0, v15
	s_and_saveexec_b64 s[2:3], vcc
	s_cbranch_execz .LBB0_1852
	s_bcnt1_i32_b64 s4, s[4:5]
	v_mov_b32_e32 v16, s4
	global_atomic_add v102, v14, v16, s[10:11] sc0
.LBB0_1852:
	s_or_b64 exec, exec, s[2:3]
.LBB0_1853:
	s_or_b64 exec, exec, s[0:1]
	v_cmp_gt_i32_e32 vcc, s30, v22
	s_and_saveexec_b64 s[0:1], vcc
	s_cbranch_execz .LBB0_1865
	s_cmp_eq_u32 s98, 1
	s_cbranch_scc1 .LBB0_1865
	v_max_i32_e32 v15, 0x240, v22
	v_sub_u32_e32 v15, v15, v22
	v_add_u32_e32 v15, 0x1ff, v15
	v_cmp_lt_u32_e32 vcc, s31, v15
	s_mov_b64 s[4:5], -1
	v_mov_b32_e32 v16, v22
	s_and_saveexec_b64 s[2:3], vcc
	s_cbranch_execz .LBB0_1862
	v_lshrrev_b32_e32 v15, 9, v15
	v_add_u32_e32 v25, 0x600, v22
	v_add_u32_e32 v24, 0x400, v22
	v_add_u32_e32 v23, 0x200, v22
	v_add_u32_e32 v16, -3, v15
	v_mov_b64_e32 v[28:29], v[24:25]
	v_cmp_lt_u32_e32 vcc, 3, v16
	v_mov_b64_e32 v[26:27], v[22:23]
	s_and_saveexec_b64 s[20:21], vcc
	s_cbranch_execz .LBB0_1859
	v_lshrrev_b32_e32 v17, 2, v16
	v_add_u32_e32 v17, 1, v17
	v_mov_b64_e32 v[28:29], v[24:25]
	v_and_b32_e32 v17, 0x7ffffffe, v17
	s_mov_b64 s[22:23], 0
	v_mov_b64_e32 v[26:27], v[22:23]

.LBB0_1865:
	s_or_b64 exec, exec, s[0:1]
	s_load_dwordx4 s[0:3], s[92:93], 0x70
	s_mov_b32 s19, s13
	s_lshl_b64 s[4:5], s[18:19], 2
	v_bfe_i32 v23, v22, 28, 1
	v_lshlrev_b32_e32 v15, 3, v22
	s_waitcnt lgkmcnt(0)
	s_add_u32 s0, s0, s4
	s_addc_u32 s1, s1, s5
	s_load_dword s60, s[0:1], 0x9000
	s_load_dword s61, s[0:1], 0xf000
	s_load_dword s62, s[0:1], 0xc000
	s_add_u32 s2, s2, s4
	s_addc_u32 s3, s3, s5
	s_load_dword s63, s[2:3], 0x3000
	s_load_dword s64, s[0:1], 0xa000
	s_load_dword s65, s[0:1], 0xd000
	s_load_dword s66, s[0:1], 0x10000
	s_load_dword s67, s[2:3], 0x4000
	v_ashrrev_i32_e32 v16, 31, v22
	v_lshrrev_b32_e32 v23, 22, v23
	v_lshrrev_b32_e32 v26, 25, v16
	v_add_u32_e32 v23, v15, v23
	v_add_u32_e32 v26, v22, v26
	v_and_b32_e32 v23, 0xfffffc00, v23
	v_ashrrev_i32_e32 v50, 7, v26
	v_sub_u32_e32 v26, v15, v23
	v_lshlrev_b32_e32 v23, 11, v50
	v_lshlrev_b32_e32 v53, 1, v26
	v_add3_u32 v23, 0, v23, v53
	s_waitcnt lgkmcnt(0)
	v_mov_b32_e32 v25, s60
	v_mov_b32_e32 v24, s61
	v_mov_b32_e32 v27, s62
	v_mov_b32_e32 v17, s63
	v_mov_b32_e32 v29, s64
	v_mov_b32_e32 v31, s65
	v_mov_b32_e32 v28, s66
	v_mov_b32_e32 v52, s67
	v_and_b32_e32 v34, 0xffff0000, v2
	v_lshlrev_b32_e32 v33, 16, v1
	v_lshlrev_b32_e32 v36, 16, v3
	v_and_b32_e32 v39, 0xffff0000, v5
	v_and_b32_e32 v38, 0xffff0000, v4
	v_lshlrev_b32_e32 v41, 16, v5
	v_lshlrev_b32_e32 v40, 16, v80
	v_mov_b32_e32 v32, v34
	v_lshlrev_b32_e32 v30, 16, v2
	v_and_b32_e32 v35, 0xffff0000, v3
	v_lshlrev_b32_e32 v37, 16, v4
	v_mov_b32_e32 v46, v36
	v_mov_b32_e32 v47, v34
	v_pk_mov_b32 v[48:49], v[40:41], v[38:39] op_sel:[1,0]
	v_and_b32_e32 v44, 0xffff0000, v6
	v_lshlrev_b32_e32 v43, 16, v81
	v_mov_b32_e32 v42, v44
	v_lshlrev_b32_e32 v62, 16, v6
	v_and_b32_e32 v45, 0xffff0000, v7
	v_cmp_gt_i32_e32 vcc, s34, v22
	v_mov_b32_e32 v54, v25
	v_pk_mul_f32 v[32:33], v[24:25], v[32:33]
	v_mad_u64_u32 v[50:51], s[4:5], v50, s42, v[26:27]
	v_lshl_add_u32 v63, v50, 1, 0
	s_load_dword s68, s[0:1], 0xb000
	s_load_dword s69, s[0:1], 0xe000
	s_load_dword s70, s[0:1], 0x11000
	s_load_dword s71, s[2:3], 0x5000
	v_mov_b32_e32 v55, v24
	v_mov_b32_e32 v26, v24
	v_pk_mul_f32 v[56:57], v[24:25], v[40:41]
	v_fma_f32 v33, v27, v30, v33
	v_pk_mul_f32 v[58:59], v[54:55], v[34:35]
	v_pk_mul_f32 v[46:47], v[26:27], v[46:47]
	v_pk_mul_f32 v[60:61], v[54:55], v[36:37]
	v_mov_b32_e32 v34, v38
	v_pk_mul_f32 v[54:55], v[54:55], v[38:39]
	v_pk_mul_f32 v[48:49], v[26:27], v[48:49]
	v_fma_f32 v26, v27, v39, v57
	v_add_f32_e32 v38, v32, v33
	v_fma_f32 v30, v25, v30, v47
	v_fma_f32 v36, v27, v36, v58
	v_fma_f32 v39, v27, v35, v60
	v_pk_mul_f32 v[32:33], v[24:25], v[34:35]
	v_fma_f32 v24, v25, v37, v49
	v_fma_f32 v25, v27, v41, v54
	v_add_f32_e32 v26, v56, v26
	v_add_f32_e32 v30, v46, v30
	v_add_f32_e32 v35, v59, v36
	v_add_f32_e32 v36, v61, v39
	v_fma_f32 v27, v27, v37, v33
	v_add_f32_e32 v24, v48, v24
	v_add_f32_e32 v25, v55, v25
	s_waitcnt lgkmcnt(0)
	v_mov_b32_e32 v51, s68
	v_mov_b32_e32 v53, s69
	v_mov_b32_e32 v50, s70
	v_mov_b32_e32 v64, s71
	v_add_f32_e32 v34, v17, v38
	v_add_f32_e32 v26, v17, v26
	v_add_f32_e32 v30, v17, v30
	v_add_f32_e32 v33, v17, v35
	v_add_f32_e32 v35, v17, v36
	v_add_f32_e32 v27, v32, v27
	v_add_f32_e32 v32, v17, v24
	v_add_f32_e32 v36, v17, v25
	v_cvt_pk_bf16_f32 v24, v34, v30
	v_cvt_pk_bf16_f32 v25, v33, v35
	v_add_f32_e32 v17, v17, v27
	v_cvt_pk_bf16_f32 v27, v36, v26
	v_cvt_pk_bf16_f32 v26, v17, v32
	ds_write_b128 v63, v[24:27] offset:128
	v_pk_mul_f32 v[24:25], v[28:29], v[42:43]
	v_lshlrev_b32_e32 v32, 16, v7
	v_fma_f32 v17, v31, v62, v25
	v_add_f32_e32 v17, v24, v17
	v_mov_b32_e32 v24, v29
	v_mov_b32_e32 v25, v28
	v_pk_mul_f32 v[26:27], v[24:25], v[44:45]
	v_lshlrev_b32_e32 v33, 16, v8
	v_fma_f32 v26, v31, v32, v26
	v_add_f32_e32 v26, v27, v26
	v_add_f32_e32 v39, v52, v26
	v_pk_mul_f32 v[26:27], v[24:25], v[32:33]
	v_mov_b32_e32 v30, v28
	v_mov_b32_e32 v34, v32
	v_mov_b32_e32 v35, v44
	v_fma_f32 v26, v31, v45, v26
	v_pk_mul_f32 v[34:35], v[30:31], v[34:35]
	v_add_f32_e32 v26, v27, v26
	v_fma_f32 v35, v29, v62, v35
	v_add_f32_e32 v32, v52, v26
	v_and_b32_e32 v26, 0xffff0000, v8
	v_add_f32_e32 v34, v34, v35
	v_mov_b32_e32 v44, v26
	v_add_f32_e32 v38, v52, v34
	v_pk_mul_f32 v[34:35], v[28:29], v[44:45]
	v_and_b32_e32 v27, 0xffff0000, v9
	v_fma_f32 v35, v31, v33, v35
	v_add_f32_e32 v34, v34, v35
	v_add_f32_e32 v40, v52, v34
	v_pk_mul_f32 v[24:25], v[24:25], v[26:27]
	v_lshlrev_b32_e32 v35, 16, v9
	v_lshlrev_b32_e32 v34, 16, v82
	v_pk_mov_b32 v[36:37], v[34:35], v[26:27] op_sel:[1,0]
	v_fma_f32 v24, v31, v35, v24
	v_pk_mul_f32 v[36:37], v[30:31], v[36:37]
	v_add_f32_e32 v24, v25, v24
	v_fma_f32 v26, v29, v33, v37
	v_add_f32_e32 v30, v52, v24
	v_pk_mul_f32 v[24:25], v[28:29], v[34:35]
	v_add_f32_e32 v26, v36, v26
	v_fma_f32 v25, v31, v27, v25
	v_add_f32_e32 v26, v52, v26
	v_add_f32_e32 v24, v24, v25
	v_add_f32_e32 v27, v52, v24
	v_cvt_pk_bf16_f32 v26, v40, v26
	v_add_f32_e32 v17, v52, v17
	v_cvt_pk_bf16_f32 v24, v17, v38
	v_cvt_pk_bf16_f32 v25, v39, v32
	v_cvt_pk_bf16_f32 v27, v30, v27
	ds_write_b128 v23, v[24:27] offset:18560
	v_and_b32_e32 v26, 0xffff0000, v10
	v_lshlrev_b32_e32 v25, 16, v83
	v_mov_b32_e32 v24, v26
	v_lshlrev_b32_e32 v17, 16, v10
	v_pk_mul_f32 v[24:25], v[50:51], v[24:25]
	v_and_b32_e32 v27, 0xffff0000, v11
	v_fma_f32 v25, v53, v17, v25
	v_add_f32_e32 v24, v24, v25
	v_add_f32_e32 v34, v64, v24
	v_mov_b32_e32 v24, v51
	v_mov_b32_e32 v25, v50
	v_pk_mul_f32 v[28:29], v[24:25], v[26:27]
	v_lshlrev_b32_e32 v30, 16, v11
	v_lshlrev_b32_e32 v31, 16, v12
	v_mov_b32_e32 v33, v26
	v_fma_f32 v26, v53, v30, v28
	v_add_f32_e32 v26, v29, v26
	v_pk_mul_f32 v[28:29], v[24:25], v[30:31]
	v_add_f32_e32 v35, v64, v26
	v_fma_f32 v26, v53, v27, v28
	v_add_f32_e32 v26, v29, v26
	v_and_b32_e32 v28, 0xffff0000, v12
	v_mov_b32_e32 v32, v30
	v_add_f32_e32 v30, v64, v26
	v_mov_b32_e32 v26, v28
	v_pk_mul_f32 v[26:27], v[50:51], v[26:27]
	v_mov_b32_e32 v52, v50
	v_fma_f32 v27, v53, v31, v27
	v_pk_mul_f32 v[32:33], v[52:53], v[32:33]
	v_and_b32_e32 v29, 0xffff0000, v13
	v_add_f32_e32 v26, v26, v27
	v_fma_f32 v17, v51, v17, v33
	v_add_f32_e32 v36, v64, v26
	v_pk_mul_f32 v[24:25], v[24:25], v[28:29]
	v_lshlrev_b32_e32 v27, 16, v13
	v_lshlrev_b32_e32 v26, 16, v84
	v_add_f32_e32 v17, v32, v17
	v_pk_mov_b32 v[32:33], v[26:27], v[28:29] op_sel:[1,0]
	v_fma_f32 v24, v53, v27, v24
	v_pk_mul_f32 v[32:33], v[52:53], v[32:33]
	v_add_f32_e32 v24, v25, v24
	v_fma_f32 v28, v51, v31, v33
	v_add_f32_e32 v31, v64, v24
	v_pk_mul_f32 v[24:25], v[50:51], v[26:27]
	v_add_f32_e32 v28, v32, v28
	v_fma_f32 v25, v53, v29, v25
	v_add_f32_e32 v24, v24, v25
	v_add_f32_e32 v27, v64, v24
	v_add_f32_e32 v17, v64, v17
	v_add_f32_e32 v28, v64, v28
	v_cvt_pk_bf16_f32 v24, v34, v17
	v_cvt_pk_bf16_f32 v25, v35, v30
	v_cvt_pk_bf16_f32 v26, v36, v28
	v_cvt_pk_bf16_f32 v27, v31, v27
	ds_write_b128 v23, v[24:27] offset:26752
	s_and_saveexec_b64 s[0:1], vcc
	s_cbranch_execz .LBB0_1867
	v_add_u32_sdwa v16, v22, v16 dst_sel:DWORD dst_unused:UNUSED_PAD src0_sel:DWORD src1_sel:BYTE_3
	v_ashrrev_i32_e32 v16, 8, v16
	v_lshlrev_b32_e32 v17, 11, v16
	v_sub_u32_e32 v15, v15, v17
	v_mad_i32_i24 v17, v16, s43, v15
	v_mul_i32_i24_e32 v16, 0x2220, v16
	v_lshlrev_b32_e32 v15, 1, v15
	v_lshl_add_u32 v17, v17, 1, 0
	v_add3_u32 v15, 0, v16, v15
	ds_write_b128 v17, v[18:21] offset:35072
	ds_write_b128 v15, v[18:21] offset:39438

.LBB0_1889:
	v_mov_b32_e32 v15, s46
	s_cbranch_execz .Lhyf_nowait_1848_0
	s_waitcnt vmcnt(0)
.Lhyf_nowait_1848_0:
	ds_write_b32 v15, v102

.LBB0_1909:
	s_and_b64 vcc, exec, s[0:1]
	s_cbranch_vccz .LBB0_1847
	v_mov_b32_e32 v22, v154
	v_mov_b32_e32 v44, 0
	v_cmp_eq_u32_e32 vcc, 0, v22
	s_and_saveexec_b64 s[0:1], vcc
	s_cbranch_execz .LBB0_1914
	s_mov_b64 s[4:5], exec
	v_mbcnt_lo_u32_b32 v15, s4, 0
	v_mbcnt_hi_u32_b32 v15, s5, v15
	v_cmp_eq_u32_e32 vcc, 0, v15
	s_and_saveexec_b64 s[2:3], vcc
	s_cbranch_execz .LBB0_1913
	s_bcnt1_i32_b64 s4, s[4:5]
	v_mov_b32_e32 v16, s4
	global_atomic_add v44, v14, v16, s[10:11] sc0
.LBB0_1913:
	s_or_b64 exec, exec, s[2:3]
.LBB0_1914:
	s_or_b64 exec, exec, s[0:1]
	v_cmp_gt_i32_e32 vcc, s49, v22
	s_and_saveexec_b64 s[0:1], vcc
	s_cbranch_execz .LBB0_1926
	s_cmp_eq_u32 s98, 2
	s_cbranch_scc1 .LBB0_1926
	v_max_i32_e32 v15, 0xf00, v22
	v_sub_u32_e32 v15, v15, v22
	v_add_u32_e32 v15, 0x1ff, v15
	v_cmp_lt_u32_e32 vcc, s31, v15
	s_mov_b64 s[4:5], -1
	v_mov_b32_e32 v16, v22
	s_and_saveexec_b64 s[2:3], vcc
	s_cbranch_execz .LBB0_1923
	v_lshrrev_b32_e32 v15, 9, v15
	s_waitcnt vmcnt(2)
	v_add_u32_e32 v25, 0x600, v22
	v_add_u32_e32 v24, 0x400, v22
	v_add_u32_e32 v23, 0x200, v22
	v_add_u32_e32 v16, -3, v15
	s_waitcnt vmcnt(1)
	v_mov_b64_e32 v[28:29], v[24:25]
	v_cmp_lt_u32_e32 vcc, 3, v16
	v_mov_b64_e32 v[26:27], v[22:23]
	s_and_saveexec_b64 s[20:21], vcc
	s_cbranch_execz .LBB0_1920
	v_lshrrev_b32_e32 v17, 2, v16
	v_add_u32_e32 v17, 1, v17
	v_mov_b64_e32 v[28:29], v[24:25]
	v_and_b32_e32 v17, 0x7ffffffe, v17
	s_mov_b64 s[22:23], 0
	v_mov_b64_e32 v[26:27], v[22:23]

.LBB0_1926:
	s_or_b64 exec, exec, s[0:1]
	s_load_dwordx4 s[4:7], s[92:93], 0x70
	s_mov_b32 s19, s13
	s_lshl_b64 s[2:3], s[18:19], 2
	v_lshlrev_b32_e32 v15, 3, v22
	v_ashrrev_i32_e32 v16, 31, v22
	s_waitcnt lgkmcnt(0)
	s_add_u32 s0, s4, s2
	s_addc_u32 s1, s5, s3
	s_load_dword s60, s[0:1], 0x9000
	s_load_dword s61, s[0:1], 0xf000
	s_load_dword s62, s[0:1], 0xa000
	s_load_dword s63, s[0:1], 0x10000
	s_load_dword s64, s[0:1], 0xc000
	s_add_u32 s2, s6, s2
	s_addc_u32 s3, s7, s3
	s_load_dword s65, s[2:3], 0x3000
	s_load_dword s66, s[0:1], 0xd000
	s_load_dword s67, s[2:3], 0x4000
	v_bfe_i32 v23, v22, 28, 1
	s_waitcnt lgkmcnt(0)
	v_mov_b32_e32 v25, s60
	v_mov_b32_e32 v24, s61
	v_mov_b32_e32 v29, s62
	v_mov_b32_e32 v28, s63
	v_mov_b32_e32 v27, s64
	v_mov_b32_e32 v17, s65
	v_mov_b32_e32 v31, s66
	v_mov_b32_e32 v45, s67
	v_lshrrev_b32_e32 v26, 27, v16
	v_add_u32_sdwa v23, v15, v23 dst_sel:DWORD dst_unused:UNUSED_PAD src0_sel:DWORD src1_sel:BYTE_3
	v_add_u32_e32 v26, v22, v26
	v_and_b32_e32 v23, 0xffffff00, v23
	v_ashrrev_i32_e32 v52, 5, v26
	v_sub_u32_e32 v26, v15, v23
	v_lshlrev_b32_e32 v23, 9, v52
	v_lshlrev_b32_e32 v55, 1, v26
	v_add3_u32 v23, 0, v23, v55
	v_and_b32_e32 v34, 0xffff0000, v2
	v_lshlrev_b32_e32 v33, 16, v1
	v_lshlrev_b32_e32 v36, 16, v3
	v_and_b32_e32 v39, 0xffff0000, v5
	v_and_b32_e32 v38, 0xffff0000, v4
	v_lshlrev_b32_e32 v41, 16, v5
	v_lshlrev_b32_e32 v40, 16, v80
	v_mov_b32_e32 v32, v34
	v_lshlrev_b32_e32 v30, 16, v2
	v_and_b32_e32 v35, 0xffff0000, v3
	v_lshlrev_b32_e32 v37, 16, v4
	v_mov_b32_e32 v48, v36
	v_mov_b32_e32 v49, v34
	v_pk_mov_b32 v[50:51], v[40:41], v[38:39] op_sel:[1,0]
	v_and_b32_e32 v47, 0xffff0000, v7
	v_and_b32_e32 v46, 0xffff0000, v6
	v_lshlrev_b32_e32 v54, 16, v6
	v_mov_b32_e32 v42, v46
	v_lshlrev_b32_e32 v43, 16, v81
	v_cmp_gt_i32_e32 vcc, s55, v22
	v_mov_b32_e32 v56, v25
	v_pk_mul_f32 v[32:33], v[24:25], v[32:33]
	v_mov_b32_e32 v57, v24
	v_pk_mul_f32 v[58:59], v[24:25], v[40:41]
	v_mad_u64_u32 v[52:53], s[4:5], v52, s54, v[26:27]
	v_lshl_add_u32 v64, v52, 1, 0
	s_load_dword s68, s[0:1], 0xb000
	s_load_dword s69, s[0:1], 0xe000
	s_load_dword s70, s[0:1], 0x11000
	s_load_dword s71, s[2:3], 0x5000
	v_mov_b32_e32 v26, v24
	v_fma_f32 v33, v27, v30, v33
	v_pk_mul_f32 v[60:61], v[56:57], v[34:35]
	v_pk_mul_f32 v[48:49], v[26:27], v[48:49]
	v_pk_mul_f32 v[62:63], v[56:57], v[36:37]
	v_mov_b32_e32 v34, v38
	v_pk_mul_f32 v[56:57], v[56:57], v[38:39]
	v_pk_mul_f32 v[50:51], v[26:27], v[50:51]
	v_fma_f32 v26, v27, v39, v59
	v_add_f32_e32 v38, v32, v33
	v_fma_f32 v30, v25, v30, v49
	v_fma_f32 v36, v27, v36, v60
	v_fma_f32 v39, v27, v35, v62
	v_pk_mul_f32 v[32:33], v[24:25], v[34:35]
	v_fma_f32 v24, v25, v37, v51
	v_fma_f32 v25, v27, v41, v56
	v_add_f32_e32 v26, v58, v26
	v_add_f32_e32 v30, v48, v30
	v_add_f32_e32 v35, v61, v36
	v_add_f32_e32 v36, v63, v39
	v_fma_f32 v27, v27, v37, v33
	v_add_f32_e32 v24, v50, v24
	v_add_f32_e32 v25, v57, v25
	s_waitcnt lgkmcnt(0)
	v_mov_b32_e32 v53, s68
	v_mov_b32_e32 v55, s69
	v_mov_b32_e32 v52, s70
	v_mov_b32_e32 v65, s71
	v_add_f32_e32 v34, v17, v38
	v_add_f32_e32 v26, v17, v26
	v_add_f32_e32 v30, v17, v30
	v_add_f32_e32 v33, v17, v35
	v_add_f32_e32 v35, v17, v36
	v_add_f32_e32 v27, v32, v27
	v_add_f32_e32 v32, v17, v24
	v_add_f32_e32 v36, v17, v25
	v_cvt_pk_bf16_f32 v24, v34, v30
	v_cvt_pk_bf16_f32 v25, v33, v35
	v_add_f32_e32 v17, v17, v27
	v_cvt_pk_bf16_f32 v27, v36, v26
	v_cvt_pk_bf16_f32 v26, v17, v32
	ds_write_b128 v64, v[24:27] offset:128
	v_mov_b32_e32 v24, v29
	v_mov_b32_e32 v25, v28
	v_pk_mul_f32 v[26:27], v[24:25], v[46:47]
	v_lshlrev_b32_e32 v32, 16, v7
	v_fma_f32 v26, v31, v32, v26
	v_lshlrev_b32_e32 v33, 16, v8
	v_add_f32_e32 v26, v27, v26
	v_add_f32_e32 v39, v45, v26
	v_pk_mul_f32 v[26:27], v[24:25], v[32:33]
	v_mov_b32_e32 v30, v28
	v_mov_b32_e32 v34, v32
	v_mov_b32_e32 v35, v46
	v_fma_f32 v26, v31, v47, v26
	v_pk_mul_f32 v[34:35], v[30:31], v[34:35]
	v_add_f32_e32 v26, v27, v26
	v_fma_f32 v35, v29, v54, v35
	v_add_f32_e32 v32, v45, v26
	v_and_b32_e32 v26, 0xffff0000, v8
	v_add_f32_e32 v34, v34, v35
	v_mov_b32_e32 v46, v26
	v_add_f32_e32 v38, v45, v34
	v_pk_mul_f32 v[34:35], v[28:29], v[46:47]
	v_and_b32_e32 v27, 0xffff0000, v9
	v_fma_f32 v35, v31, v33, v35
	v_add_f32_e32 v34, v34, v35
	v_add_f32_e32 v40, v45, v34
	v_pk_mul_f32 v[24:25], v[24:25], v[26:27]
	v_lshlrev_b32_e32 v35, 16, v9
	v_lshlrev_b32_e32 v34, 16, v82
	v_pk_mov_b32 v[36:37], v[34:35], v[26:27] op_sel:[1,0]
	v_fma_f32 v24, v31, v35, v24
	v_pk_mul_f32 v[36:37], v[30:31], v[36:37]
	v_add_f32_e32 v24, v25, v24
	v_fma_f32 v26, v29, v33, v37
	v_add_f32_e32 v30, v45, v24
	v_pk_mul_f32 v[24:25], v[28:29], v[34:35]
	v_pk_mul_f32 v[42:43], v[28:29], v[42:43]
	v_add_f32_e32 v26, v36, v26
	v_fma_f32 v25, v31, v27, v25
	v_fma_f32 v17, v31, v54, v43
	v_add_f32_e32 v26, v45, v26
	v_add_f32_e32 v24, v24, v25
	v_add_f32_e32 v17, v42, v17
	v_add_f32_e32 v27, v45, v24
	v_cvt_pk_bf16_f32 v26, v40, v26
	v_add_f32_e32 v17, v45, v17
	v_cvt_pk_bf16_f32 v24, v17, v38
	v_cvt_pk_bf16_f32 v25, v39, v32
	v_cvt_pk_bf16_f32 v27, v30, v27
	ds_write_b128 v23, v[24:27] offset:25088
	v_and_b32_e32 v26, 0xffff0000, v10
	v_lshlrev_b32_e32 v25, 16, v83
	v_mov_b32_e32 v24, v26
	v_lshlrev_b32_e32 v17, 16, v10
	v_pk_mul_f32 v[24:25], v[52:53], v[24:25]
	v_and_b32_e32 v27, 0xffff0000, v11
	v_fma_f32 v25, v55, v17, v25
	v_add_f32_e32 v24, v24, v25
	v_add_f32_e32 v34, v65, v24
	v_mov_b32_e32 v24, v53
	v_mov_b32_e32 v25, v52
	v_pk_mul_f32 v[28:29], v[24:25], v[26:27]
	v_lshlrev_b32_e32 v30, 16, v11
	v_lshlrev_b32_e32 v31, 16, v12
	v_mov_b32_e32 v33, v26
	v_fma_f32 v26, v55, v30, v28
	v_add_f32_e32 v26, v29, v26
	v_pk_mul_f32 v[28:29], v[24:25], v[30:31]
	v_add_f32_e32 v35, v65, v26
	v_fma_f32 v26, v55, v27, v28
	v_add_f32_e32 v26, v29, v26
	v_and_b32_e32 v28, 0xffff0000, v12
	v_mov_b32_e32 v32, v30
	v_add_f32_e32 v30, v65, v26
	v_mov_b32_e32 v26, v28
	v_pk_mul_f32 v[26:27], v[52:53], v[26:27]
	v_mov_b32_e32 v54, v52
	v_fma_f32 v27, v55, v31, v27
	v_pk_mul_f32 v[32:33], v[54:55], v[32:33]
	v_and_b32_e32 v29, 0xffff0000, v13
	v_add_f32_e32 v26, v26, v27
	v_fma_f32 v17, v53, v17, v33
	v_add_f32_e32 v36, v65, v26
	v_pk_mul_f32 v[24:25], v[24:25], v[28:29]
	v_lshlrev_b32_e32 v27, 16, v13
	v_lshlrev_b32_e32 v26, 16, v84
	v_add_f32_e32 v17, v32, v17
	v_pk_mov_b32 v[32:33], v[26:27], v[28:29] op_sel:[1,0]
	v_fma_f32 v24, v55, v27, v24
	v_pk_mul_f32 v[32:33], v[54:55], v[32:33]
	v_add_f32_e32 v24, v25, v24
	v_fma_f32 v28, v53, v31, v33
	v_add_f32_e32 v31, v65, v24
	v_pk_mul_f32 v[24:25], v[52:53], v[26:27]
	v_add_f32_e32 v28, v32, v28
	v_fma_f32 v25, v55, v29, v25
	v_add_f32_e32 v24, v24, v25
	v_add_f32_e32 v27, v65, v24
	v_add_f32_e32 v17, v65, v17
	v_add_f32_e32 v28, v65, v28
	v_cvt_pk_bf16_f32 v24, v34, v17
	v_cvt_pk_bf16_f32 v25, v35, v30
	v_cvt_pk_bf16_f32 v26, v36, v28
	v_cvt_pk_bf16_f32 v27, v31, v27
	ds_write_b128 v23, v[24:27] offset:33280
	s_and_saveexec_b64 s[0:1], vcc
	s_cbranch_execz .LBB0_1928
	v_lshrrev_b32_e32 v16, 26, v16
	v_add_u32_e32 v16, v22, v16
	v_ashrrev_i32_e32 v17, 6, v16
	v_lshlrev_b32_e32 v16, 9, v17
	v_sub_u32_e32 v16, v15, v16
	v_mad_u64_u32 v[24:25], s[2:3], v17, s56, v[16:17]
	v_lshl_add_u32 v15, v24, 1, 0
	ds_write_b128 v15, v[18:21] offset:41600
	v_mul_lo_u32 v15, v17, s57
	v_lshlrev_b32_e32 v16, 1, v16
	v_add3_u32 v15, 0, v15, v16
	ds_write_b128 v15, v[18:21] offset:42894
